# MLA blocks: V-fragment LDS reads issued up front with the K-fragment reads (QK MFMA chains uninterrupted); first block's K fragments 1-8 in v[214:245]
# baseline (speedup 1.0000x reference)
; #define LAS __attribute__((address_space(3)))
; #define MFMA32(a, b, c) __builtin_amdgcn_mfma_f32_32x32x16_bf16((a), (b), (c), 0, 0, 0)
; template <int DQK, int DV, bool CAUSAL, int KT, bool PRIO>
; DI void attn_unit(const bf16_t* Qb, int qpitch, const bf16_t* Kb, int kpitch, const bf16_t* Vtb, int vpitch, bf16_t* Ob, int opitch, int q0, int nt, LAS unsigned char* lds, float kbound, const float* qgain, const int* qpos, float qscale) {
;     ...
;                 if (PRIO) {
;                     constexpr int KSN = DQK / 16, NDB = DV / 32;
;                     f32x16 s0 = negm, s1 = negm;
;                     const LAS unsigned char* kb = lds + buf * KBUF + (64 * hf + r) * KS + h * 16;
;                     const LAS unsigned char* vb = lds + VOFF + buf * VBUF + r * VS + h * 8 + 128 * hf;
;                     bf16x8 kf0[KSN], kf1[KSN], vf[4][NDB];
; #pragma unroll
;                     for (int ks = 0; ks < KSN; ++ks) { kf0[ks] = *(const LAS bf16x8*)(kb + ks * 32); kf1[ks] = *(const LAS bf16x8*)(kb + 32 * KS + ks * 32); }
;                     __builtin_amdgcn_sched_barrier(0); __builtin_amdgcn_s_setprio(1); __builtin_amdgcn_sched_barrier(0);
; #pragma unroll
;                     for (int ks = 0; ks < KSN; ++ks) { s0 = MFMA32(kf0[ks], qf[ks], s0); s1 = MFMA32(kf1[ks], qf[ks], s1); }
;                     __builtin_amdgcn_sched_barrier(0); __builtin_amdgcn_s_setprio(0); __builtin_amdgcn_sched_barrier(0);
; #pragma unroll
;                     for (int q4 = 0; q4 < 4; ++q4)
; #pragma unroll
;                         for (int d = 0; d < NDB; ++d) { const LAS unsigned char* vp = vb + d * 32 * VS + q4 * 32;
;                             const s16x4 lo = *(const LAS s16x4*)vp, hi = *(const LAS s16x4*)(vp + 16); vf[q4][d] = (bf16x8){lo[0], lo[1], lo[2], lo[3], hi[0], hi[1], hi[2], hi[3]}; }
;                     if (CAUSAL && key0 + 63 > qlo) {
; #pragma unroll
;                         for (int i = 0; i < 16; ++i) { const int key = key0 + (i & 3) + 8 * (i >> 2) + 4 * h; if (key > qabs) s0[i] = -1e30f; if (key + 32 > qabs) s1[i] = -1e30f; }
.LBB0_1495:
	ds_read_b128 v[214:217], v194
	ds_read_b128 v[218:221], v194 offset:32
	ds_read_b128 v[222:225], v194 offset:6656
	ds_read_b128 v[226:229], v194 offset:6688
	ds_read_b128 v[230:233], v194 offset:64
	ds_read_b128 v[234:237], v194 offset:96
	ds_read_b128 v[238:241], v194 offset:6720
	ds_read_b128 v[242:245], v194 offset:6752
	ds_read_b128 v[198:201], v194 offset:128
	ds_read_b128 v[202:205], v194 offset:160
	ds_read_b128 v[206:209], v194 offset:6784
	ds_read_b128 v[210:213], v194 offset:6816
	ds_read_b128 v[152:155], v14
	ds_read_b128 v[140:143], v14 offset:32
	ds_read_b128 v[156:159], v15
	ds_read_b128 v[148:151], v15 offset:32
	ds_read_b128 v[144:147], v14 offset:64
	ds_read_b128 v[10:13], v15 offset:64
	ds_read_b128 v[6:9], v14 offset:96
	ds_read_b128 v[2:5], v15 offset:96
	global_load_dwordx4 v[96:99], v[172:173], off
	global_load_dwordx4 v[100:103], v[170:171], off
	global_load_dwordx4 v[104:107], v[168:169], off
	global_load_dwordx4 v[108:111], v[166:167], off
	global_load_dwordx4 v[112:115], v[164:165], off
	v_lshl_add_u64 v[164:165], v[164:165], 0, s[14:15]
	v_lshl_add_u64 v[166:167], v[166:167], 0, s[14:15]
	v_lshl_add_u64 v[168:169], v[168:169], 0, s[16:17]
	v_lshl_add_u64 v[170:171], v[170:171], 0, s[16:17]
	v_lshl_add_u64 v[172:173], v[172:173], 0, s[16:17]
	s_setprio 1
	s_setprio 0
	s_waitcnt lgkmcnt(8)
	v_mfma_f32_32x32x16_bf16 v[80:95], v[214:217], v[116:119], v[48:63]
	s_cmp_le_i32 s71, s69
	v_mfma_f32_32x32x16_bf16 v[64:79], v[222:225], v[116:119], v[48:63]
	v_mfma_f32_32x32x16_bf16 v[80:95], v[218:221], v[120:123], v[80:95]
	v_mfma_f32_32x32x16_bf16 v[64:79], v[226:229], v[120:123], v[64:79]
	v_mfma_f32_32x32x16_bf16 v[80:95], v[230:233], v[124:127], v[80:95]
	v_mfma_f32_32x32x16_bf16 v[64:79], v[238:241], v[124:127], v[64:79]
	v_mfma_f32_32x32x16_bf16 v[80:95], v[234:237], v[128:131], v[80:95]
	v_mfma_f32_32x32x16_bf16 v[64:79], v[242:245], v[128:131], v[64:79]
	v_mfma_f32_32x32x16_bf16 v[80:95], v[198:201], v[132:135], v[80:95]
	v_mfma_f32_32x32x16_bf16 v[64:79], v[206:209], v[132:135], v[64:79]
	v_mfma_f32_32x32x16_bf16 v[80:95], v[202:205], v[136:139], v[80:95]
	v_mfma_f32_32x32x16_bf16 v[64:79], v[210:213], v[136:139], v[64:79]
	ds_read_b128 v[214:217], v194 offset:13312
	ds_read_b128 v[218:221], v194 offset:13344
	ds_read_b128 v[222:225], v194 offset:19968
	ds_read_b128 v[226:229], v194 offset:20000
	ds_read_b128 v[230:233], v194 offset:13376
	ds_read_b128 v[234:237], v194 offset:13408
	ds_read_b128 v[238:241], v194 offset:20032
	ds_read_b128 v[242:245], v194 offset:20064
	s_cbranch_scc1 .LBB0_1497
	v_add_u32_e32 v195, s71, v180
	v_subrev_u32_e32 v198, 31, v195
	v_subrev_u32_e32 v197, 63, v195
	v_cmp_le_i32_e32 vcc, v198, v189
	s_nop 6
	v_cndmask_b32_e32 v64, v177, v64, vcc
	v_cmp_lt_i32_e32 vcc, v197, v189
	s_nop 1
	v_cndmask_b32_e32 v81, v177, v81, vcc
	v_cmp_le_i32_e32 vcc, v197, v189
	v_subrev_u32_e32 v197, 30, v195
	s_nop 0
	v_cndmask_b32_e32 v80, v177, v80, vcc
	v_cmp_le_i32_e32 vcc, v197, v189
	v_subrev_u32_e32 v197, 61, v195
	s_nop 0
	v_cndmask_b32_e32 v65, v177, v65, vcc
	v_cmp_le_i32_e32 vcc, v197, v189
	v_subrev_u32_e32 v197, 29, v195
	s_nop 0
	v_cndmask_b32_e32 v82, v177, v82, vcc
	v_cmp_le_i32_e32 vcc, v197, v189
	v_subrev_u32_e32 v197, 60, v195
	s_nop 0
	v_cndmask_b32_e32 v66, v177, v66, vcc
	v_cmp_le_i32_e32 vcc, v197, v189
	v_subrev_u32_e32 v197, 28, v195
	s_nop 0
	v_cndmask_b32_e32 v83, v177, v83, vcc
	v_cmp_le_i32_e32 vcc, v197, v189
	v_subrev_u32_e32 v197, 55, v195
	s_nop 0
	v_cndmask_b32_e32 v67, v177, v67, vcc
	v_cmp_le_i32_e32 vcc, v197, v189
	v_subrev_u32_e32 v197, 23, v195
	s_nop 0
	v_cndmask_b32_e32 v84, v177, v84, vcc
	v_cmp_le_i32_e32 vcc, v197, v189
	v_subrev_u32_e32 v197, 54, v195
	s_nop 0
	v_cndmask_b32_e32 v68, v177, v68, vcc
	v_cmp_le_i32_e32 vcc, v197, v189
	v_subrev_u32_e32 v197, 22, v195
	s_nop 0
	v_cndmask_b32_e32 v85, v177, v85, vcc
	v_cmp_le_i32_e32 vcc, v197, v189
	v_subrev_u32_e32 v197, 53, v195
	s_nop 0
	v_cndmask_b32_e32 v69, v177, v69, vcc
	v_cmp_le_i32_e32 vcc, v197, v189
	v_subrev_u32_e32 v197, 21, v195
	s_nop 0
	v_cndmask_b32_e32 v86, v177, v86, vcc
	v_cmp_le_i32_e32 vcc, v197, v189
	v_subrev_u32_e32 v197, 52, v195
	s_nop 0
	v_cndmask_b32_e32 v70, v177, v70, vcc
	v_cmp_le_i32_e32 vcc, v197, v189
	v_subrev_u32_e32 v197, 20, v195
	s_nop 0
	v_cndmask_b32_e32 v87, v177, v87, vcc
	v_cmp_le_i32_e32 vcc, v197, v189
	v_subrev_u32_e32 v197, 47, v195
	s_nop 0
	v_cndmask_b32_e32 v71, v177, v71, vcc
	v_cmp_le_i32_e32 vcc, v197, v189
	v_add_u32_e32 v197, -15, v195
	s_nop 0
	v_cndmask_b32_e32 v88, v177, v88, vcc
	v_cmp_le_i32_e32 vcc, v197, v189
	v_subrev_u32_e32 v197, 46, v195
	s_nop 0
	v_cndmask_b32_e32 v72, v177, v72, vcc
	v_cmp_le_i32_e32 vcc, v197, v189
	v_add_u32_e32 v197, -14, v195
	s_nop 0
	v_cndmask_b32_e32 v89, v177, v89, vcc
	v_cmp_le_i32_e32 vcc, v197, v189
	v_subrev_u32_e32 v197, 45, v195
	s_nop 0
	v_cndmask_b32_e32 v73, v177, v73, vcc
	v_cmp_le_i32_e32 vcc, v197, v189
	v_add_u32_e32 v197, -13, v195
	s_nop 0
	v_cndmask_b32_e32 v90, v177, v90, vcc
	v_cmp_le_i32_e32 vcc, v197, v189
	v_subrev_u32_e32 v197, 44, v195
	s_nop 0
	v_cndmask_b32_e32 v74, v177, v74, vcc
	v_cmp_le_i32_e32 vcc, v197, v189
	v_add_u32_e32 v197, -12, v195
	s_nop 0
	v_cndmask_b32_e32 v91, v177, v91, vcc
	v_cmp_le_i32_e32 vcc, v197, v189
	v_subrev_u32_e32 v197, 39, v195
	s_nop 0
	v_cndmask_b32_e32 v75, v177, v75, vcc
	v_cmp_le_i32_e32 vcc, v197, v189
	v_add_u32_e32 v197, -7, v195
	s_nop 0
	v_cndmask_b32_e32 v92, v177, v92, vcc
	v_cmp_le_i32_e32 vcc, v197, v189
	v_subrev_u32_e32 v197, 38, v195
	s_nop 0
	v_cndmask_b32_e32 v76, v177, v76, vcc
	v_cmp_le_i32_e32 vcc, v197, v189
	v_add_u32_e32 v197, -6, v195
	s_nop 0
	v_cndmask_b32_e32 v93, v177, v93, vcc
	v_cmp_le_i32_e32 vcc, v197, v189
	v_subrev_u32_e32 v197, 37, v195
	s_nop 0
	v_cndmask_b32_e32 v77, v177, v77, vcc
	v_cmp_le_i32_e32 vcc, v197, v189
	v_add_u32_e32 v197, -5, v195
	s_nop 0
	v_cndmask_b32_e32 v94, v177, v94, vcc
	v_cmp_le_i32_e32 vcc, v197, v189
	v_subrev_u32_e32 v197, 36, v195
	v_add_u32_e32 v195, -4, v195
	v_cndmask_b32_e32 v78, v177, v78, vcc
	v_cmp_le_i32_e32 vcc, v197, v189
	s_nop 1
	v_cndmask_b32_e32 v95, v177, v95, vcc
	v_cmp_le_i32_e32 vcc, v195, v189
	s_nop 1
	v_cndmask_b32_e32 v79, v177, v79, vcc

; #define LAS __attribute__((address_space(3)))
; #define MFMA32(a, b, c) __builtin_amdgcn_mfma_f32_32x32x16_bf16((a), (b), (c), 0, 0, 0)
; template <int DQK, int DV, bool CAUSAL, int KT, bool PRIO>
; DI void attn_unit(const bf16_t* Qb, int qpitch, const bf16_t* Kb, int kpitch, const bf16_t* Vtb, int vpitch, bf16_t* Ob, int opitch, int q0, int nt, LAS unsigned char* lds, float kbound, const float* qgain, const int* qpos, float qscale) {
;     ...
;             const int key0 = kt * KT + 64 * hf;
;             if (!CAUSAL || key0 <= qlo + 31) {
;                 if (PRIO) {
;                     constexpr int KSN = DQK / 16, NDB = DV / 32;
;                     f32x16 s0 = negm, s1 = negm;
;                     const LAS unsigned char* kb = lds + buf * KBUF + (64 * hf + r) * KS + h * 16;
;                     const LAS unsigned char* vb = lds + VOFF + buf * VBUF + r * VS + h * 8 + 128 * hf;
;                     bf16x8 kf0[KSN], kf1[KSN], vf[4][NDB];
; #pragma unroll
;                     for (int ks = 0; ks < KSN; ++ks) { kf0[ks] = *(const LAS bf16x8*)(kb + ks * 32); kf1[ks] = *(const LAS bf16x8*)(kb + 32 * KS + ks * 32); }
;                     __builtin_amdgcn_sched_barrier(0); __builtin_amdgcn_s_setprio(1); __builtin_amdgcn_sched_barrier(0);
; #pragma unroll
;                     for (int ks = 0; ks < KSN; ++ks) { s0 = MFMA32(kf0[ks], qf[ks], s0); s1 = MFMA32(kf1[ks], qf[ks], s1); }
;                     __builtin_amdgcn_sched_barrier(0); __builtin_amdgcn_s_setprio(0); __builtin_amdgcn_sched_barrier(0);
; #pragma unroll
;                     for (int q4 = 0; q4 < 4; ++q4)
; #pragma unroll
;                         for (int d = 0; d < NDB; ++d) { const LAS unsigned char* vp = vb + d * 32 * VS + q4 * 32;
;                             const s16x4 lo = *(const LAS s16x4*)vp, hi = *(const LAS s16x4*)(vp + 16); vf[q4][d] = (bf16x8){lo[0], lo[1], lo[2], lo[3], hi[0], hi[1], hi[2], hi[3]}; }
;                     if (CAUSAL && key0 + 63 > qlo) {
; #pragma unroll
;                         for (int i = 0; i < 16; ++i) { const int key = key0 + (i & 3) + 8 * (i >> 2) + 4 * h; if (key > qabs) s0[i] = -1e30f; if (key + 32 > qabs) s1[i] = -1e30f; }
.LBB0_1505:
	ds_read_b128 v[198:201], v194 offset:13440
	ds_read_b128 v[202:205], v194 offset:13472
	ds_read_b128 v[206:209], v194 offset:20096
	ds_read_b128 v[210:213], v194 offset:20128
	ds_read_b128 v[156:159], v14 offset:128
	ds_read_b128 v[140:143], v14 offset:160
	ds_read_b128 v[152:155], v15 offset:128
	ds_read_b128 v[148:151], v15 offset:160
	ds_read_b128 v[144:147], v14 offset:192
	ds_read_b128 v[10:13], v15 offset:192
	ds_read_b128 v[6:9], v14 offset:224
	ds_read_b128 v[2:5], v15 offset:224
	s_setprio 1
	s_setprio 0
	s_waitcnt lgkmcnt(8)
	v_mfma_f32_32x32x16_bf16 v[80:95], v[214:217], v[116:119], v[48:63]
	s_add_i32 s12, s71, 64
	s_cmp_le_i32 s12, s69
	v_mfma_f32_32x32x16_bf16 v[64:79], v[222:225], v[116:119], v[48:63]
	v_mfma_f32_32x32x16_bf16 v[80:95], v[218:221], v[120:123], v[80:95]
	v_mfma_f32_32x32x16_bf16 v[64:79], v[226:229], v[120:123], v[64:79]
	v_mfma_f32_32x32x16_bf16 v[80:95], v[230:233], v[124:127], v[80:95]
	v_mfma_f32_32x32x16_bf16 v[64:79], v[238:241], v[124:127], v[64:79]
	v_mfma_f32_32x32x16_bf16 v[80:95], v[234:237], v[128:131], v[80:95]
	v_mfma_f32_32x32x16_bf16 v[64:79], v[242:245], v[128:131], v[64:79]
	v_mfma_f32_32x32x16_bf16 v[80:95], v[198:201], v[132:135], v[80:95]
	v_mfma_f32_32x32x16_bf16 v[64:79], v[206:209], v[132:135], v[64:79]
	v_mfma_f32_32x32x16_bf16 v[80:95], v[202:205], v[136:139], v[80:95]
	v_mfma_f32_32x32x16_bf16 v[64:79], v[210:213], v[136:139], v[64:79]
	s_cbranch_scc1 .LBB0_1507
	v_add_u32_e32 v14, s71, v180
	v_add_u32_e32 v194, 33, v14
	v_add_u32_e32 v15, 1, v14
	v_cmp_le_i32_e32 vcc, v194, v189
	s_nop 6
	v_cndmask_b32_e32 v64, v177, v64, vcc
	v_cmp_lt_i32_e32 vcc, v15, v189
	s_nop 1
	v_cndmask_b32_e32 v81, v177, v81, vcc
	v_cmp_le_i32_e32 vcc, v15, v189
	v_add_u32_e32 v15, 34, v14
	s_nop 0
	v_cndmask_b32_e32 v80, v177, v80, vcc
	v_cmp_le_i32_e32 vcc, v15, v189
	v_add_u32_e32 v15, 3, v14
	s_nop 0
	v_cndmask_b32_e32 v65, v177, v65, vcc
	v_cmp_le_i32_e32 vcc, v15, v189
	v_add_u32_e32 v15, 35, v14
	s_nop 0
	v_cndmask_b32_e32 v82, v177, v82, vcc
	v_cmp_le_i32_e32 vcc, v15, v189
	v_add_u32_e32 v15, 4, v14
	s_nop 0
	v_cndmask_b32_e32 v66, v177, v66, vcc
	v_cmp_le_i32_e32 vcc, v15, v189
	v_add_u32_e32 v15, 36, v14
	s_nop 0
	v_cndmask_b32_e32 v83, v177, v83, vcc
	v_cmp_le_i32_e32 vcc, v15, v189
	v_add_u32_e32 v15, 9, v14
	s_nop 0
	v_cndmask_b32_e32 v67, v177, v67, vcc
	v_cmp_le_i32_e32 vcc, v15, v189
	v_add_u32_e32 v15, 41, v14
	s_nop 0
	v_cndmask_b32_e32 v84, v177, v84, vcc
	v_cmp_le_i32_e32 vcc, v15, v189
	v_add_u32_e32 v15, 10, v14
	s_nop 0
	v_cndmask_b32_e32 v68, v177, v68, vcc
	v_cmp_le_i32_e32 vcc, v15, v189
	v_add_u32_e32 v15, 42, v14
	s_nop 0
	v_cndmask_b32_e32 v85, v177, v85, vcc
	v_cmp_le_i32_e32 vcc, v15, v189
	v_add_u32_e32 v15, 11, v14
	s_nop 0
	v_cndmask_b32_e32 v69, v177, v69, vcc
	v_cmp_le_i32_e32 vcc, v15, v189
	v_add_u32_e32 v15, 43, v14
	s_nop 0
	v_cndmask_b32_e32 v86, v177, v86, vcc
	v_cmp_le_i32_e32 vcc, v15, v189
	v_add_u32_e32 v15, 12, v14
	s_nop 0
	v_cndmask_b32_e32 v70, v177, v70, vcc
	v_cmp_le_i32_e32 vcc, v15, v189
	v_add_u32_e32 v15, 44, v14
	s_nop 0
	v_cndmask_b32_e32 v87, v177, v87, vcc
	v_cmp_le_i32_e32 vcc, v15, v189
	v_add_u32_e32 v15, 17, v14
	s_nop 0
	v_cndmask_b32_e32 v71, v177, v71, vcc
	v_cmp_le_i32_e32 vcc, v15, v189
	v_add_u32_e32 v15, 49, v14
	s_nop 0
	v_cndmask_b32_e32 v88, v177, v88, vcc
	v_cmp_le_i32_e32 vcc, v15, v189
	v_add_u32_e32 v15, 18, v14
	s_nop 0
	v_cndmask_b32_e32 v72, v177, v72, vcc
	v_cmp_le_i32_e32 vcc, v15, v189
	v_add_u32_e32 v15, 50, v14
	s_nop 0
	v_cndmask_b32_e32 v89, v177, v89, vcc
	v_cmp_le_i32_e32 vcc, v15, v189
	v_add_u32_e32 v15, 19, v14
	s_nop 0
	v_cndmask_b32_e32 v73, v177, v73, vcc
	v_cmp_le_i32_e32 vcc, v15, v189
	v_add_u32_e32 v15, 51, v14
	s_nop 0
	v_cndmask_b32_e32 v90, v177, v90, vcc
	v_cmp_le_i32_e32 vcc, v15, v189
	v_add_u32_e32 v15, 20, v14
	s_nop 0
	v_cndmask_b32_e32 v74, v177, v74, vcc
	v_cmp_le_i32_e32 vcc, v15, v189
	v_add_u32_e32 v15, 52, v14
	s_nop 0
	v_cndmask_b32_e32 v91, v177, v91, vcc
	v_cmp_le_i32_e32 vcc, v15, v189
	v_add_u32_e32 v15, 25, v14
	s_nop 0
	v_cndmask_b32_e32 v75, v177, v75, vcc
	v_cmp_le_i32_e32 vcc, v15, v189
	v_add_u32_e32 v15, 57, v14
	s_nop 0
	v_cndmask_b32_e32 v92, v177, v92, vcc
	v_cmp_le_i32_e32 vcc, v15, v189
	v_add_u32_e32 v15, 26, v14
	s_nop 0
	v_cndmask_b32_e32 v76, v177, v76, vcc
	v_cmp_le_i32_e32 vcc, v15, v189
	v_add_u32_e32 v15, 58, v14
	s_nop 0
	v_cndmask_b32_e32 v93, v177, v93, vcc
	v_cmp_le_i32_e32 vcc, v15, v189
	v_add_u32_e32 v15, 27, v14
	s_nop 0
	v_cndmask_b32_e32 v77, v177, v77, vcc
	v_cmp_le_i32_e32 vcc, v15, v189
	v_add_u32_e32 v15, 59, v14
	s_nop 0
	v_cndmask_b32_e32 v94, v177, v94, vcc
	v_cmp_le_i32_e32 vcc, v15, v189
	v_add_u32_e32 v15, 28, v14
	v_add_u32_e32 v14, 60, v14
	v_cndmask_b32_e32 v78, v177, v78, vcc
	v_cmp_le_i32_e32 vcc, v15, v189
	s_nop 1
	v_cndmask_b32_e32 v95, v177, v95, vcc
	v_cmp_le_i32_e32 vcc, v14, v189
	s_nop 1
	v_cndmask_b32_e32 v79, v177, v79, vcc

; #define LAS __attribute__((address_space(3)))
; template <int DQK, int DV, bool CAUSAL, int KT, bool PRIO>
; DI void attn_unit(const bf16_t* Qb, int qpitch, const bf16_t* Kb, int kpitch, const bf16_t* Vtb, int vpitch, bf16_t* Ob, int opitch, int q0, int nt, LAS unsigned char* lds, float kbound, const float* qgain, const int* qpos, float qscale) {
;     ...
;     auto lstore = [&](int buf) {
; #pragma unroll
;         for (int i = 0; i < NKR; ++i) { const int c = tid + i * 512; if (NKC % 512 == 0 || c < NKC) *(LAS u32x4*)(lds + buf * KBUF + (c / KCH) * KS + (c % KCH) * 16) = kreg[i]; }
; #pragma unroll
;         for (int i = 0; i < NVR; ++i) { const int c = tid + i * 512; LAS unsigned char* p = lds + VOFF + buf * VBUF + (c / VCH) * VS + (c % VCH) * 16;
;             *(LAS u32x2*)p = (u32x2){vreg[i].x, vreg[i].y}; *(LAS u32x2*)(p + 8) = (u32x2){vreg[i].z, vreg[i].w}; }
;     };
;     ...
;                     float ps = 0.f;
; #pragma unroll
;                     for (int i = 0; i < 16; ++i) { s0[i] = __builtin_amdgcn_exp2f(s0[i]); ps += s0[i]; asm volatile("" : "+v"(ps)); }
; #pragma unroll
;                     for (int i = 0; i < 16; ++i) { s1[i] = __builtin_amdgcn_exp2f(s1[i]); ps += s1[i]; asm volatile("" : "+v"(ps)); }
;                     lrun += ps;
;                     bf16x8 pf[4];
; #pragma unroll
;                     for (int sf = 0; sf < 2; ++sf) {
;                         u32x4 pw; pw.x = pk2(s0[8 * sf], s0[8 * sf + 1]); pw.y = pk2(s0[8 * sf + 2], s0[8 * sf + 3]); pw.z = pk2(s0[8 * sf + 4], s0[8 * sf + 5]); pw.w = pk2(s0[8 * sf + 6], s0[8 * sf + 7]); pf[sf] = __builtin_bit_cast(bf16x8, pw);
;                         u32x4 pv; pv.x = pk2(s1[8 * sf], s1[8 * sf + 1]); pv.y = pk2(s1[8 * sf + 2], s1[8 * sf + 3]); pv.z = pk2(s1[8 * sf + 4], s1[8 * sf + 5]); pv.w = pk2(s1[8 * sf + 6], s1[8 * sf + 7]); pf[2 + sf] = __builtin_bit_cast(bf16x8, pv);
;                     }
;                     __builtin_amdgcn_sched_barrier(0); __builtin_amdgcn_s_setprio(1); __builtin_amdgcn_sched_barrier(0);
; #pragma unroll
;                     for (int q4 = 0; q4 < 4; ++q4)
; #pragma unroll
;                         for (int d = 0; d < NDB; ++d) o[d] = MFMA32(vf[q4][d], pf[q4], o[d]);
;                     __builtin_amdgcn_sched_barrier(0); __builtin_amdgcn_s_setprio(0); __builtin_amdgcn_sched_barrier(0);
.LBB0_1514:
	s_nop 7
	v_exp_f32_e32 v14, v80
	v_exp_f32_e32 v15, v81
	v_exp_f32_e32 v80, v82
	v_exp_f32_e32 v81, v83
	v_add_f32_e32 v82, 0, v14
	v_exp_f32_e32 v83, v84
	v_add_f32_e32 v82, v15, v82
	v_exp_f32_e32 v84, v85
	v_add_f32_e32 v82, v80, v82
	v_exp_f32_e32 v85, v86
	v_add_f32_e32 v82, v81, v82
	v_exp_f32_e32 v86, v87
	v_add_f32_e32 v82, v83, v82
	v_exp_f32_e32 v87, v88
	v_add_f32_e32 v82, v84, v82
	v_exp_f32_e32 v88, v89
	v_add_f32_e32 v82, v85, v82
	v_exp_f32_e32 v89, v90
	v_add_f32_e32 v82, v86, v82
	v_exp_f32_e32 v90, v91
	v_add_f32_e32 v82, v87, v82
	v_exp_f32_e32 v91, v92
	v_add_f32_e32 v82, v88, v82
	v_exp_f32_e32 v92, v93
	v_add_f32_e32 v82, v89, v82
	v_exp_f32_e32 v93, v94
	v_add_f32_e32 v82, v90, v82
	v_exp_f32_e32 v94, v95
	v_add_f32_e32 v82, v91, v82
	v_exp_f32_e32 v95, v64
	v_add_f32_e32 v82, v92, v82
	v_exp_f32_e32 v194, v66
	v_add_f32_e32 v82, v93, v82
	v_exp_f32_e32 v195, v67
	v_add_f32_e32 v64, v94, v82
	v_exp_f32_e32 v82, v65
	v_exp_f32_e32 v197, v68
	v_add_f32_e32 v64, v95, v64
	v_exp_f32_e32 v198, v69
	v_add_f32_e32 v64, v82, v64
	v_exp_f32_e32 v199, v70
	v_add_f32_e32 v64, v194, v64
	v_exp_f32_e32 v71, v71
	v_add_f32_e32 v64, v195, v64
	v_exp_f32_e32 v200, v72
	v_add_f32_e32 v64, v197, v64
	v_exp_f32_e32 v201, v73
	v_add_f32_e32 v64, v198, v64
	v_exp_f32_e32 v202, v74
	v_add_f32_e32 v64, v199, v64
	v_exp_f32_e32 v203, v75
	v_add_f32_e32 v64, v71, v64
	v_exp_f32_e32 v204, v76
	v_add_f32_e32 v64, v200, v64
	v_exp_f32_e32 v205, v77
	v_add_f32_e32 v64, v201, v64
	v_exp_f32_e32 v206, v78
	v_add_f32_e32 v64, v202, v64
	v_exp_f32_e32 v79, v79
	v_add_f32_e32 v64, v203, v64
	v_cvt_pk_bf16_f32 v65, v80, v81
	v_add_f32_e32 v64, v204, v64
	v_cvt_pk_bf16_f32 v66, v83, v84
	v_add_f32_e32 v64, v205, v64
	v_cvt_pk_bf16_f32 v67, v85, v86
	v_add_f32_e32 v64, v206, v64
	v_cvt_pk_bf16_f32 v68, v95, v82
	v_add_f32_e32 v207, v79, v64
	v_cvt_pk_bf16_f32 v64, v14, v15
	v_cvt_pk_bf16_f32 v69, v194, v195
	v_cvt_pk_bf16_f32 v70, v197, v198
	v_cvt_pk_bf16_f32 v71, v199, v71
	v_cvt_pk_bf16_f32 v72, v87, v88
	v_cvt_pk_bf16_f32 v73, v89, v90
	v_cvt_pk_bf16_f32 v74, v91, v92
	v_cvt_pk_bf16_f32 v75, v93, v94
	v_cvt_pk_bf16_f32 v76, v200, v201
	v_cvt_pk_bf16_f32 v77, v202, v203
	v_cvt_pk_bf16_f32 v78, v204, v205
	v_cvt_pk_bf16_f32 v79, v206, v79
	s_setprio 1
	s_waitcnt lgkmcnt(0)
	s_waitcnt vmcnt(0)
	v_mfma_f32_32x32x16_bf16 v[32:47], v[156:159], v[64:67], v[32:47]
	v_add_f32_e32 v0, v0, v207
	s_xor_b32 s100, s75, 1
	s_mul_i32 s101, s100, 0x6800
	v_add3_u32 v250, s101, v178, v179
	v_mfma_f32_32x32x16_bf16 v[16:31], v[152:155], v[64:67], v[16:31]
	ds_write_b128 v250, v[96:99]
	v_add3_u32 v251, s101, v181, v182
	s_mulk_i32 s100, 0xdc00
	v_mfma_f32_32x32x16_bf16 v[32:47], v[140:143], v[72:75], v[32:47]
	ds_write_b128 v251, v[100:103]
	v_add3_u32 v250, s101, v183, v184
	s_add_i32 s101, s101, s100
	v_mfma_f32_32x32x16_bf16 v[16:31], v[148:151], v[72:75], v[16:31]
	ds_write_b128 v250, v[104:107]
	v_add_u32_e32 v251, s101, v185
	v_add3_u32 v251, v251, v186, s57
	v_mfma_f32_32x32x16_bf16 v[32:47], v[144:147], v[68:71], v[32:47]
	ds_write2_b64 v251, v[108:109], v[110:111] offset1:2
	v_add_u32_e32 v250, s101, v187
	v_add3_u32 v250, v250, v188, s57
	v_mfma_f32_32x32x16_bf16 v[16:31], v[10:13], v[68:71], v[16:31]
	ds_write2_b64 v250, v[112:113], v[114:115] offset1:2
	v_mfma_f32_32x32x16_bf16 v[32:47], v[6:9], v[76:79], v[32:47]
	v_mfma_f32_32x32x16_bf16 v[16:31], v[2:5], v[76:79], v[16:31]
	s_setprio 0
	s_branch .LBB0_1493
	s_nop 0
	s_nop 0
	s_nop 0
	s_nop 0
	s_nop 0
	s_nop 0
	s_nop 0
	s_nop 0
	s_nop 0
	s_nop 0
	s_nop 0
	s_nop 0
	s_nop 0
	s_nop 0
